# RMSNorm and final norm rows remapped XCD-local; norm->inproj (layer 0) and out->final-norm barriers XCD-local too
# baseline (speedup 1.0000x reference)
.LBB0_178:
	v_writelane_b32 v252, s2, 23
	s_and_b64 s[0:1], s[2:3], exec
	s_waitcnt vmcnt(2)
	v_mov_b32_e32 v0, v197
	v_writelane_b32 v252, s3, 24
	v_readlane_b32 s0, v253, 8
	v_readlane_b32 s1, v253, 9
	s_cselect_b32 s1, s1, s95
	s_cselect_b32 s0, s0, s94
	v_writelane_b32 v252, s0, 25
	v_readlane_b32 s6, v253, 14
	v_readlane_b32 s7, v253, 15
	v_writelane_b32 v252, s1, 26
	s_mov_b64 s[0:1], 0
	v_readlane_b32 s2, v253, 10
	v_ashrrev_i32_e32 v1, 6, v0
	s_and_b32 s25, s52, 7
	s_lshl_b32 s25, s25, 11
	s_lshr_b32 s26, s52, 3
	s_lshl_b32 s26, s26, 3
	s_add_i32 s25, s25, s26
	v_add_u32_e32 v36, s25, v1
	v_cmp_gt_i32_e32 vcc, s71, v36
	v_readlane_b32 s3, v253, 11
	v_readlane_b32 s4, v253, 12
	v_readlane_b32 s5, v253, 13
	v_readlane_b32 s8, v253, 16
	v_readlane_b32 s9, v253, 17
	v_readlane_b32 s10, v253, 18
	v_readlane_b32 s11, v253, 19
	v_readlane_b32 s12, v253, 20
	v_readlane_b32 s13, v253, 21
	v_readlane_b32 s14, v253, 22
	v_readlane_b32 s15, v253, 23
	s_and_saveexec_b64 s[6:7], vcc
	s_cbranch_execz .LBB0_189
	s_add_u32 s2, s96, s0
	s_mul_i32 s90, s76, 0x3000
	s_addc_u32 s3, s97, s1
	s_lshl_b64 s[0:1], s[90:91], 2
	s_add_u32 s0, s2, s0
	s_addc_u32 s1, s3, s1
	s_add_u32 s8, s0, 0x10ac0000
	s_addc_u32 s9, s1, 0
	v_lshlrev_b32_e32 v0, 2, v0
	v_cmp_lt_i32_e32 vcc, v230, v219
	s_add_u32 s10, s2, 0xb000000
	v_and_b32_e32 v38, 0xfc, v0
	v_cndmask_b32_e32 v0, v218, v230, vcc
	v_cmp_lt_i32_e32 vcc, v229, v219
	s_addc_u32 s11, s3, 0
	s_lshl_b32 s90, s76, 10
	v_readlane_b32 s12, v253, 8
	v_lshlrev_b32_e32 v39, 2, v0
	v_cndmask_b32_e32 v0, v218, v229, vcc
	v_cmp_lt_i32_e32 vcc, v226, v219
	s_lshl_b64 s[0:1], s[90:91], 2
	v_readlane_b32 s18, v253, 14
	v_lshlrev_b32_e32 v45, 2, v0
	v_cndmask_b32_e32 v0, v218, v226, vcc
	v_cmp_lt_i32_e32 vcc, v224, v219
	v_readlane_b32 s19, v253, 15
	s_add_u32 s0, s18, s0
	v_readlane_b32 s2, v252, 25
	v_lshlrev_b32_e32 v47, 2, v0
	v_cndmask_b32_e32 v0, v218, v224, vcc
	v_cmp_lt_i32_e32 vcc, v223, v219
	s_addc_u32 s1, s19, s1
	v_lshlrev_b32_e32 v194, 2, v38
	v_readlane_b32 s3, v252, 26
	v_lshlrev_b32_e32 v49, 2, v0
	v_cndmask_b32_e32 v0, v218, v223, vcc
	v_cmp_lt_i32_e32 vcc, v222, v219
	v_readlane_b32 s13, v253, 9
	v_lshl_add_u64 v[40:41], s[2:3], 0, v[194:195]
	v_lshlrev_b32_e32 v64, 2, v0
	v_cndmask_b32_e32 v0, v218, v222, vcc
	v_lshl_add_u64 v[42:43], s[0:1], 0, v[194:195]
	v_lshlrev_b32_e32 v194, 1, v38
	v_lshlrev_b32_e32 v65, 2, v0
	v_or_b32_e32 v44, 0x100, v38
	v_or_b32_e32 v46, 0x200, v38
	v_or_b32_e32 v48, 0x300, v38
	v_lshl_add_u64 v[50:51], s[10:11], 0, v[194:195]
	s_mov_b64 s[12:13], 0
	v_lshlrev_b32_e32 v194, 2, v38
	v_readlane_b32 s14, v253, 10
	v_readlane_b32 s15, v253, 11
	v_readlane_b32 s16, v253, 12
	v_readlane_b32 s17, v253, 13
	v_readlane_b32 s20, v253, 16
	v_readlane_b32 s21, v253, 17
	v_readlane_b32 s22, v253, 18
	v_readlane_b32 s23, v253, 19
	v_readlane_b32 s24, v253, 20
	v_readlane_b32 s25, v253, 21
	v_readlane_b32 s26, v253, 22
	v_readlane_b32 s27, v253, 23
	s_branch .LBB0_181
.LBB0_180:
	s_or_b64 exec, exec, s[0:1]
	v_add_u32_e32 v36, 0x200, v36
	s_and_b32 s0, s52, 7
	s_lshl_b32 s0, s0, 11
	s_or_b32 s0, s0, 0x7ff
	v_cmp_lt_i32_e32 vcc, s0, v36
	s_or_b64 s[12:13], vcc, s[12:13]
	s_andn2_b64 exec, exec, s[12:13]
	s_cbranch_execz .LBB0_189
.LBB0_181:
	v_ashrrev_i32_e32 v37, 31, v36
	v_add_u32_e32 v58, 0x100, v36
	v_lshlrev_b64 v[0:1], 12, v[36:37]
	v_cmp_gt_i32_e32 vcc, s71, v58
	v_lshl_add_u64 v[0:1], v[40:41], 0, v[0:1]
	global_load_dwordx4 v[28:31], v[0:1], off
	global_load_dwordx4 v[20:23], v[0:1], off offset:1024
	global_load_dwordx4 v[12:15], v[0:1], off offset:2048
	global_load_dwordx4 v[4:7], v[0:1], off offset:3072
	v_cndmask_b32_e32 v56, v36, v58, vcc
	v_ashrrev_i32_e32 v57, 31, v56
	v_lshlrev_b64 v[0:1], 12, v[56:57]
	v_lshl_add_u64 v[0:1], v[40:41], 0, v[0:1]
	global_load_dwordx4 v[24:27], v[0:1], off
	global_load_dwordx4 v[16:19], v[0:1], off offset:1024
	global_load_dwordx4 v[8:11], v[0:1], off offset:2048
	s_nop 0
	global_load_dwordx4 v[0:3], v[0:1], off offset:3072
	v_ashrrev_i32_e32 v52, 12, v36
	v_mul_i32_i24_e32 v52, 0xc00, v52
	v_ashrrev_i32_e32 v53, 31, v52
	v_lshl_add_u64 v[52:53], v[52:53], 2, s[8:9]
	s_mov_b64 s[2:3], 0x1000
	v_lshl_add_u64 v[54:55], v[52:53], 0, s[2:3]
	v_lshl_add_u64 v[52:53], v[52:53], 0, v[194:195]
	global_load_dwordx4 v[32:35], v[42:43], off
	v_lshl_add_u64 v[60:61], v[54:55], 0, v[194:195]
	global_load_dwordx4 v[68:71], v[52:53], off
	global_load_dwordx4 v[72:75], v[60:61], off
	s_mov_b32 s0, 0x3a800000
	v_ashrrev_i32_e32 v59, 31, v58
	v_lshlrev_b64 v[58:59], 11, v[58:59]
	s_waitcnt vmcnt(10)
	v_mov_b32_e32 v62, v29
	s_waitcnt vmcnt(9)
	v_mov_b32_e32 v63, v21
	s_waitcnt vmcnt(8)
	v_mov_b32_e32 v80, v13
	s_waitcnt vmcnt(7)
	v_mov_b32_e32 v81, v5
	v_mov_b32_e32 v60, v28
	v_mov_b32_e32 v61, v20
	v_mov_b32_e32 v78, v12
	v_mov_b32_e32 v79, v4
	v_pk_mul_f32 v[62:63], v[62:63], v[62:63]
	v_pk_mul_f32 v[80:81], v[80:81], v[80:81]
	v_mov_b32_e32 v66, v30
	v_mov_b32_e32 v67, v22
	v_pk_fma_f32 v[60:61], v[60:61], v[60:61], v[62:63]
	v_pk_fma_f32 v[62:63], v[78:79], v[78:79], v[80:81]
	s_waitcnt vmcnt(6)
	v_mov_b32_e32 v80, v25
	s_waitcnt vmcnt(5)
	v_mov_b32_e32 v81, v17
	v_mov_b32_e32 v78, v24
	v_mov_b32_e32 v79, v16
	s_waitcnt vmcnt(4)
	v_mov_b32_e32 v90, v9
	s_waitcnt vmcnt(3)
	v_mov_b32_e32 v91, v1
	v_pk_fma_f32 v[60:61], v[66:67], v[66:67], v[60:61]
	v_pk_mul_f32 v[66:67], v[80:81], v[80:81]
	v_mov_b32_e32 v76, v31
	v_mov_b32_e32 v77, v23
	v_mov_b32_e32 v86, v26
	v_mov_b32_e32 v87, v18
	v_mov_b32_e32 v88, v8
	v_mov_b32_e32 v89, v0
	v_pk_mul_f32 v[80:81], v[90:91], v[90:91]
	v_pk_fma_f32 v[66:67], v[78:79], v[78:79], v[66:67]
	v_mov_b32_e32 v82, v14
	v_mov_b32_e32 v83, v6
	v_mov_b32_e32 v92, v27
	v_mov_b32_e32 v93, v19
	v_mov_b32_e32 v94, v10
	v_mov_b32_e32 v95, v2
	v_pk_fma_f32 v[60:61], v[76:77], v[76:77], v[60:61]
	v_pk_fma_f32 v[76:77], v[88:89], v[88:89], v[80:81]
	v_pk_fma_f32 v[66:67], v[86:87], v[86:87], v[66:67]
	v_mov_b32_e32 v84, v15
	v_mov_b32_e32 v85, v7
	v_mov_b32_e32 v96, v11
	v_mov_b32_e32 v97, v3
	v_pk_fma_f32 v[62:63], v[82:83], v[82:83], v[62:63]
	v_pk_fma_f32 v[76:77], v[94:95], v[94:95], v[76:77]
	v_pk_fma_f32 v[66:67], v[92:93], v[92:93], v[66:67]
	v_pk_fma_f32 v[62:63], v[84:85], v[84:85], v[62:63]
	v_mov_b32_e32 v79, v60
	v_pk_fma_f32 v[76:77], v[96:97], v[96:97], v[76:77]
	v_mov_b32_e32 v78, v66
	v_mov_b32_e32 v60, v67
	v_mov_b32_e32 v81, v62
	v_mov_b32_e32 v80, v76
	v_pk_add_f32 v[60:61], v[78:79], v[60:61]
	v_mov_b32_e32 v62, v77
	v_pk_add_f32 v[60:61], v[60:61], v[80:81]
	s_waitcnt vmcnt(0)
	v_add_f32_e32 v72, 1.0, v72
	v_pk_add_f32 v[60:61], v[60:61], v[62:63]
	ds_bpermute_b32 v63, v39, v61
	ds_bpermute_b32 v62, v39, v60
	v_add_f32_e32 v73, 1.0, v73
	v_add_f32_e32 v74, 1.0, v74
	v_add_f32_e32 v75, 1.0, v75
	s_waitcnt lgkmcnt(0)
	v_pk_add_f32 v[60:61], v[60:61], v[62:63]
	ds_bpermute_b32 v63, v45, v61
	ds_bpermute_b32 v62, v45, v60
	s_waitcnt lgkmcnt(0)
	v_pk_add_f32 v[60:61], v[60:61], v[62:63]
	ds_bpermute_b32 v63, v47, v61
	ds_bpermute_b32 v62, v47, v60
	s_waitcnt lgkmcnt(0)
	v_pk_add_f32 v[62:63], v[60:61], v[62:63]
	ds_bpermute_b32 v67, v49, v63
	ds_bpermute_b32 v66, v49, v62
	v_lshlrev_b64 v[60:61], 11, v[36:37]
	v_ashrrev_i32_e32 v37, 12, v56
	v_lshl_add_u64 v[56:57], s[10:11], 0, v[58:59]
	v_mul_i32_i24_e32 v58, 0xc00, v37
	s_waitcnt lgkmcnt(0)
	v_pk_add_f32 v[62:63], v[62:63], v[66:67]
	ds_bpermute_b32 v67, v64, v63
	ds_bpermute_b32 v66, v64, v62
	v_ashrrev_i32_e32 v59, 31, v58
	v_lshl_add_u64 v[60:61], v[50:51], 0, v[60:61]
	v_lshl_add_u64 v[58:59], v[58:59], 2, s[8:9]
	s_waitcnt lgkmcnt(0)
	v_pk_add_f32 v[66:67], v[62:63], v[66:67]
	ds_bpermute_b32 v77, v65, v67
	ds_bpermute_b32 v76, v65, v66
	v_lshl_add_u64 v[62:63], v[58:59], 0, s[2:3]
	s_waitcnt lgkmcnt(0)
	v_pk_add_f32 v[66:67], v[66:67], v[76:77]
	s_nop 0
	v_pk_fma_f32 v[66:67], v[66:67], s[0:1], v[196:197] op_sel_hi:[1,0,0]
	s_nop 0
	v_mul_f32_e32 v37, 0x4b800000, v67
	v_cmp_gt_f32_e64 s[0:1], s72, v67
	v_mul_f32_e32 v76, 0x4b800000, v66
	v_cmp_gt_f32_e64 s[4:5], s72, v66
	v_cndmask_b32_e64 v37, v67, v37, s[0:1]
	v_rsq_f32_e32 v37, v37
	v_cndmask_b32_e64 v66, v66, v76, s[4:5]
	v_rsq_f32_e32 v67, v66
	v_mul_f32_e32 v66, 0x45800000, v37
	v_cndmask_b32_e64 v66, v37, v66, s[0:1]
	v_mul_f32_e32 v28, v28, v66
	v_mul_f32_e32 v29, v29, v66
	v_mul_f32_e32 v28, v32, v28
	v_mul_f32_e32 v30, v30, v66
	v_mul_f32_e32 v31, v31, v66
	v_mul_f32_e32 v29, v33, v29
	v_fma_f32 v28, v72, v28, v68
	v_mul_f32_e32 v76, 0x45800000, v67
	v_mul_f32_e32 v30, v34, v30
	v_mul_f32_e32 v31, v35, v31
	v_fma_f32 v29, v73, v29, v69
	v_cvt_pk_bf16_f32 v28, v28, v29
	v_cndmask_b32_e64 v37, v67, v76, s[4:5]
	v_fma_f32 v30, v74, v30, v70
	v_fmac_f32_e32 v71, v75, v31
	v_cvt_pk_bf16_f32 v29, v30, v71
	global_store_dwordx2 v[60:61], v[28:29], off
	v_lshlrev_b32_e32 v28, 1, v38
	s_and_saveexec_b64 s[0:1], vcc
	s_cbranch_execz .LBB0_183
	v_lshl_add_u64 v[30:31], v[62:63], 0, v[194:195]
	global_load_dwordx4 v[68:71], v[30:31], off
	v_lshl_add_u64 v[30:31], v[58:59], 0, v[194:195]
	global_load_dwordx4 v[72:75], v[30:31], off
	v_mul_f32_e32 v24, v24, v37
	v_mul_f32_e32 v25, v25, v37
	v_mul_f32_e32 v26, v26, v37
	v_mul_f32_e32 v27, v27, v37
	v_mul_f32_e32 v24, v32, v24
	v_mul_f32_e32 v25, v33, v25
	v_mul_f32_e32 v26, v34, v26
	v_mov_b32_e32 v29, v195
	v_mul_f32_e32 v27, v35, v27
	s_waitcnt vmcnt(1)
	v_add_f32_e32 v30, 1.0, v68
	v_add_f32_e32 v31, 1.0, v69
	v_add_f32_e32 v32, 1.0, v70
	v_add_f32_e32 v33, 1.0, v71
	s_waitcnt vmcnt(0)
	v_fma_f32 v24, v24, v30, v72
	v_fma_f32 v25, v25, v31, v73
	v_fma_f32 v26, v26, v32, v74
	v_fmac_f32_e32 v75, v27, v33
	v_cvt_pk_bf16_f32 v24, v24, v25
	v_cvt_pk_bf16_f32 v25, v26, v75
	v_lshl_add_u64 v[26:27], v[56:57], 0, v[28:29]
	global_store_dwordx2 v[26:27], v[24:25], off

.LBB0_221:
	s_andn2_saveexec_b64 s[6:7], s[6:7]
	s_cbranch_execz .LBB0_241
	s_mov_b64 s[6:7], exec
	v_readfirstlane_b32 s3, v254
	s_nop 3
	s_cmp_eq_u32 s3, 0
	s_cbranch_scc0 .Lxl_glob_222
	v_readlane_b32 s3, v252, 23
	s_nop 3
	s_cmp_lg_u32 s3, 0
	s_cbranch_scc1 .LBB0_238
.Lxl_glob_222:
	buffer_wbl2 sc1
	s_waitcnt lgkmcnt(0)
	s_waitcnt vmcnt(0)
	v_mbcnt_lo_u32_b32 v1, s6, 0
	v_mbcnt_hi_u32_b32 v1, s7, v1
	v_cmp_eq_u32_e32 vcc, 0, v1
	s_and_saveexec_b64 s[8:9], vcc
	s_cbranch_execz .LBB0_224
	s_bcnt1_i32_b64 s3, s[6:7]
	v_mov_b32_e32 v2, s3
	global_atomic_add v2, v220, v2, s[4:5] offset:1024 sc0

.LBB0_840:
	s_andn2_saveexec_b64 s[6:7], s[6:7]
	s_cbranch_execz .LBB0_177
	s_mov_b64 s[6:7], exec
	v_readfirstlane_b32 s3, v254
	s_nop 3
	s_cmp_eq_u32 s3, 0
	s_cbranch_scc0 .Lxl_glob_841
	v_readlane_b32 s3, v252, 23
	s_nop 3
	s_cmp_lg_u32 s3, 0
	s_cbranch_scc0 .LBB0_857

.LBB0_859:
	s_movk_i32 s2, 0x4000
	s_waitcnt vmcnt(2)
	v_ashrrev_i32_e32 v0, 6, v197
	s_and_b32 s0, s52, 7
	s_lshl_b32 s0, s0, 11
	s_lshr_b32 s1, s52, 3
	s_lshl_b32 s1, s1, 3
	s_add_i32 s0, s0, s1
	v_add_u32_e32 v0, s0, v0
	s_mov_b64 s[0:1], 0
	v_cmp_gt_i32_e32 vcc, s2, v0
	s_and_saveexec_b64 s[2:3], vcc
	s_cbranch_execz .LBB0_862
	v_lshlrev_b32_e32 v1, 4, v197
	v_cmp_lt_i32_e32 vcc, v230, v219
	s_waitcnt vmcnt(1)
	v_and_b32_e32 v4, 0x3f0, v1
	v_mov_b32_e32 v5, 0
	v_cndmask_b32_e32 v1, v218, v230, vcc
	v_cmp_lt_i32_e32 vcc, v229, v219
	v_lshlrev_b32_e32 v6, 2, v1
	v_lshl_add_u64 v[2:3], s[92:93], 0, v[4:5]
	v_cndmask_b32_e32 v1, v218, v229, vcc
	v_cmp_lt_i32_e32 vcc, v226, v219
	v_lshlrev_b32_e32 v7, 2, v1
	v_lshl_add_u64 v[4:5], s[94:95], 0, v[4:5]
	v_cndmask_b32_e32 v1, v218, v226, vcc
	v_cmp_lt_i32_e32 vcc, v224, v219
	v_lshlrev_b32_e32 v8, 2, v1
	v_mov_b32_e32 v12, 0x358637bd
	v_cndmask_b32_e32 v1, v218, v224, vcc
	v_cmp_lt_i32_e32 vcc, v223, v219
	v_lshlrev_b32_e32 v9, 2, v1
	s_mov_b32 s2, 0x800000
	v_cndmask_b32_e32 v1, v218, v223, vcc
	v_cmp_lt_i32_e32 vcc, v222, v219
	v_lshlrev_b32_e32 v10, 2, v1
	s_and_b32 s3, s52, 7
	s_lshl_b32 s3, s3, 11
	s_or_b32 s3, s3, 0x7ff
	v_cndmask_b32_e32 v1, v218, v222, vcc
	v_lshlrev_b32_e32 v11, 2, v1
.LBB0_861:
	v_ashrrev_i32_e32 v1, 31, v0
	v_lshlrev_b64 v[14:15], 12, v[0:1]
	v_lshl_add_u64 v[34:35], v[4:5], 0, v[14:15]
	global_load_dwordx4 v[14:17], v[34:35], off
	global_load_dwordx4 v[18:21], v[34:35], off offset:1024
	global_load_dwordx4 v[22:25], v[34:35], off offset:2048
	global_load_dwordx4 v[26:29], v[34:35], off offset:3072
	global_load_dwordx4 v[30:33], v[2:3], off
	v_add_u32_e32 v0, 0x100, v0
	s_waitcnt vmcnt(4)
	v_mov_b32_e32 v38, v15
	s_waitcnt vmcnt(3)
	v_mov_b32_e32 v39, v19
	v_mov_b32_e32 v36, v14
	v_mov_b32_e32 v37, v18
	s_waitcnt vmcnt(2)
	v_mov_b32_e32 v46, v23
	s_waitcnt vmcnt(1)
	v_mov_b32_e32 v47, v27
	v_pk_mul_f32 v[38:39], v[38:39], v[38:39]
	v_mov_b32_e32 v40, v16
	v_mov_b32_e32 v41, v20
	v_mov_b32_e32 v44, v22
	v_mov_b32_e32 v45, v26
	v_pk_mul_f32 v[46:47], v[46:47], v[46:47]
	v_pk_fma_f32 v[36:37], v[36:37], v[36:37], v[38:39]
	v_mov_b32_e32 v42, v17
	v_mov_b32_e32 v43, v21
	v_mov_b32_e32 v48, v24
	v_mov_b32_e32 v49, v28
	v_pk_fma_f32 v[38:39], v[44:45], v[44:45], v[46:47]
	v_pk_fma_f32 v[36:37], v[40:41], v[40:41], v[36:37]
	v_mov_b32_e32 v50, v25
	v_mov_b32_e32 v51, v29
	v_pk_fma_f32 v[38:39], v[48:49], v[48:49], v[38:39]
	v_pk_fma_f32 v[36:37], v[42:43], v[42:43], v[36:37]
	v_pk_fma_f32 v[38:39], v[50:51], v[50:51], v[38:39]
	v_add_f32_e32 v1, v36, v37
	v_add_f32_e32 v1, v1, v38
	v_add_f32_e32 v1, v1, v39
	ds_bpermute_b32 v13, v6, v1
	s_waitcnt lgkmcnt(0)
	v_add_f32_e32 v1, v1, v13
	ds_bpermute_b32 v13, v7, v1
	s_waitcnt lgkmcnt(0)
	v_add_f32_e32 v1, v1, v13
	ds_bpermute_b32 v13, v8, v1
	s_waitcnt lgkmcnt(0)
	v_add_f32_e32 v1, v1, v13
	ds_bpermute_b32 v13, v9, v1
	s_waitcnt lgkmcnt(0)
	v_add_f32_e32 v1, v1, v13
	ds_bpermute_b32 v13, v10, v1
	s_waitcnt lgkmcnt(0)
	v_add_f32_e32 v1, v1, v13
	ds_bpermute_b32 v13, v11, v1
	s_waitcnt lgkmcnt(0)
	v_add_f32_e32 v1, v1, v13
	v_fmamk_f32 v1, v1, 0x3a800000, v12
	v_mul_f32_e32 v13, 0x4b800000, v1
	v_cmp_gt_f32_e32 vcc, s2, v1
	s_nop 1
	v_cndmask_b32_e32 v1, v1, v13, vcc
	v_rsq_f32_e32 v1, v1
	s_nop 0
	v_mul_f32_e32 v13, 0x45800000, v1
	v_cndmask_b32_e32 v36, v1, v13, vcc
	v_pk_mul_f32 v[14:15], v[14:15], v[36:37] op_sel_hi:[1,0]
	v_pk_mul_f32 v[16:17], v[16:17], v[36:37] op_sel_hi:[1,0]
	s_waitcnt vmcnt(0)
	v_pk_mul_f32 v[14:15], v[30:31], v[14:15]
	v_pk_mul_f32 v[16:17], v[32:33], v[16:17]
	global_store_dwordx4 v[34:35], v[14:17], off
	global_load_dwordx4 v[14:17], v[2:3], off offset:1024
	v_pk_mul_f32 v[20:21], v[20:21], v[36:37] op_sel_hi:[1,0]
	v_pk_mul_f32 v[18:19], v[18:19], v[36:37] op_sel_hi:[1,0]
	v_cmp_lt_i32_e32 vcc, s3, v0
	s_or_b64 s[0:1], vcc, s[0:1]
	s_waitcnt vmcnt(0)
	v_pk_mul_f32 v[14:15], v[14:15], v[18:19]
	v_pk_mul_f32 v[16:17], v[16:17], v[20:21]
	global_store_dwordx4 v[34:35], v[14:17], off offset:1024
	global_load_dwordx4 v[14:17], v[2:3], off offset:2048
	v_pk_mul_f32 v[18:19], v[24:25], v[36:37] op_sel_hi:[1,0]
	v_pk_mul_f32 v[20:21], v[22:23], v[36:37] op_sel_hi:[1,0]
	s_waitcnt vmcnt(0)
	v_pk_mul_f32 v[16:17], v[16:17], v[18:19]
	v_pk_mul_f32 v[14:15], v[14:15], v[20:21]
	global_store_dwordx4 v[34:35], v[14:17], off offset:2048
	global_load_dwordx4 v[14:17], v[2:3], off offset:3072
	v_pk_mul_f32 v[18:19], v[28:29], v[36:37] op_sel_hi:[1,0]
	v_pk_mul_f32 v[20:21], v[26:27], v[36:37] op_sel_hi:[1,0]
	s_waitcnt vmcnt(0)
	v_pk_mul_f32 v[16:17], v[16:17], v[18:19]
	v_pk_mul_f32 v[14:15], v[14:15], v[20:21]
	global_store_dwordx4 v[34:35], v[14:17], off offset:3072
	s_andn2_b64 exec, exec, s[0:1]
	s_cbranch_execnz .LBB0_861
